# k20
# speedup vs baseline: 1.0056x; 1.0056x over previous
; #define STAGE_A(Ak_, b, h) do { const char* _s = (Ak_) + (h) * sHA; \
;     glds16(lds0 + ((b) * 2 + (h)) * (HT * 2), voffA, _s); glds16(lds0 + ((b) * 2 + (h)) * (HT * 2) + 8192, voffA, _s + s2A); } while (0)
; #define STAGE_B(Bk_, Bkh_, vh_, b, h) do { const char* _s = (h) ? (Bkh_) : (Bk_); const unsigned _v0 = (h) ? (vh_)[0] : voffB, _v1 = (h) ? (vh_)[1] : voffB; const long _d = (h) ? s2Bh : s2B; \
;     glds16(lds0 + (4 + (b) * 2 + (h)) * (HT * 2), _v0, _s); glds16(lds0 + (4 + (b) * 2 + (h)) * (HT * 2) + 8192, _v1, _s + _d); } while (0)
; #define LDA(dst, b, h) for (int m = 0; m < 4; ++m) for (int k = 0; k < 2; ++k) \
;     dst[m][k] = *reinterpret_cast<const bf16x8*>((char*)SA(b, h) + lds_byte(wr * 64 + m * 16 + fr, k * 32 + fq * 8))
; #define LDB(dst, b, h) for (int n = 0; n < 2; ++n) for (int k = 0; k < 2; ++k) \
;     dst[n][k] = *reinterpret_cast<const bf16x8*>((char*)SB(b, h) + lds_byte(wc * 32 + n * 16 + fr, k * 32 + fq * 8))
; #define MMA(ai, bj, At_, Bt_) do { __builtin_amdgcn_s_setprio(1); \
;     for (int m = 0; m < 4; ++m) for (int n = 0; n < 2; ++n) for (int k = 0; k < 2; ++k) \
;       acc[ai][bj][m][n] = __builtin_amdgcn_mfma_f32_16x16x32_bf16(At_[m][k], Bt_[n][k], acc[ai][bj][m][n], 0, 0, 0); \
;     __builtin_amdgcn_s_setprio(0); } while (0)
; #define WAIT_L(n) asm volatile("s_waitcnt lgkmcnt(" #n ")" ::: "memory")
; template <int EPI>
; __device__ __forceinline__ void gemm_phase(const GemmDesc d, u16* shm, unsigned sx, unsigned srank, unsigned snloc) {
;     ...
;       for (int kt = 0; kt < nt; kt += 2) {
;         const bool lastk = (kt + 2 >= nt);
;         const char* A1 = Au + (long)(kt + 1) * sKA;
;         const char* A2 = lastk ? Aun : Au + (long)(kt + 2) * sKA;
;         const char* B2 = lastk ? Bun : Bu + (long)(kt + 2) * sKB;
;         const char* B2h = lastk ? Bunh : Buh + (long)(kt + 2) * sKB;
;         const unsigned vh[2] = {lastk ? voffBhn[0] : voffBh[0], lastk ? voffBhn[1] : voffBh[1]};
;         const char* A3 = A2 + sKA; const char* B3 = B2 + sKB; const char* B3h = B2h + sKB;
;         LDB(B0, 0, 0); SCHED; LDA(At, 0, 0); STAGE_A(A1, 1, 1);
;         WAIT_L(8); BAR; MMA(0, 0, At, B0); BAR; SCHED;
;         LDB(B1, 0, 1); STAGE_B(B2, B2h, vh, 0, 0);
;         BAR; MMA(0, 1, At, B1); BAR;
;         LDA(At, 0, 1); STAGE_A(A2, 0, 0);
;         BAR; MMA(1, 0, At, B0); BAR; SCHED;
;     ...
;       if (wr == 1) BAR;
.LBB0_1447:
	s_add_i32 s21, s20, 2
	s_add_u32 s0, s34, 0xfffc0080
	s_addc_u32 s1, s35, -1
	s_cmp_lt_u32 s20, 14
	s_cselect_b32 s94, s90, s16
	s_cselect_b32 s51, s1, s15
	s_cselect_b32 s50, s0, s14
	s_cselect_b32 s95, s91, s17
	s_cselect_b32 s47, s93, s25
	s_cselect_b32 s46, s92, s24
	s_add_u32 s40, s94, 0x80
	s_addc_u32 s41, s95, 0
	s_add_u32 s22, s50, 0x80
	s_addc_u32 s23, s51, 0
	s_add_u32 s96, s34, 0x20000
	s_addc_u32 s97, s35, 0
	s_add_u32 s0, s94, 0x20000
	s_addc_u32 s1, s95, 0
	s_add_u32 s52, s50, 0x20000
	s_addc_u32 s53, s51, 0
	s_add_u32 s48, s46, 0x20000
	s_addc_u32 s49, s47, 0
	s_add_u32 s44, s50, 0x40000
	s_addc_u32 s45, s51, 0
	s_add_u32 s28, s50, 0x60000
	s_addc_u32 s29, s51, 0
	s_add_u32 s42, s94, 0x20080
	s_addc_u32 s43, s95, 0
	s_add_u32 s30, s50, 0x20080
	s_addc_u32 s31, s51, 0
	s_add_u32 s18, s46, 0x80
	s_addc_u32 s19, s47, 0
	s_add_u32 s4, s46, 0x20080
	s_addc_u32 s5, s47, 0
	s_add_u32 s38, s34, 0x100
	s_addc_u32 s39, s35, 0
	s_add_u32 s90, s90, 0x100
	s_addc_u32 s91, s91, 0
	s_add_u32 s92, s92, 0x100
	s_addc_u32 s93, s93, 0
	s_cmp_eq_u32 s70, 0
	s_cbranch_scc1 .Lgu_rs_skip
	s_and_b64 vcc, exec, s[6:7]
	s_cbranch_vccz .Lgu_rs_skip
	s_barrier
.Lgu_rs_skip:
	ds_read_b128 v[140:143], v131
	ds_read_b128 v[144:147], v131 offset:1024
	ds_read_b128 v[148:151], v131 offset:2048
	ds_read_b128 v[152:155], v131 offset:3072
	ds_read_b128 v[156:159], v132
	ds_read_b128 v[160:163], v132 offset:1024
	ds_read_b128 v[164:167], v133
	ds_read_b128 v[168:171], v133 offset:1024
	ds_read_b128 v[172:175], v134
	ds_read_b128 v[178:181], v134 offset:1024
	ds_read_b128 v[190:193], v135
	ds_read_b128 v[194:197], v135 offset:1024
	s_mov_b32 m0, s79
	s_nop 0
	global_load_lds_dwordx4 v130, s[34:35]
	s_mov_b32 m0, s80
	s_nop 0
	global_load_lds_dwordx4 v130, s[96:97]
	s_waitcnt lgkmcnt(8)
	s_barrier
	s_setprio 1
	s_waitcnt lgkmcnt(7)
	v_mfma_f32_16x16x32_bf16 v[124:127], v[156:159], v[140:143], 0
	v_mfma_f32_16x16x32_bf16 v[116:119], v[156:159], v[148:151], 0
	s_waitcnt lgkmcnt(5)
	v_mfma_f32_16x16x32_bf16 v[108:111], v[164:167], v[140:143], 0
	v_mfma_f32_16x16x32_bf16 v[100:103], v[164:167], v[148:151], 0
	s_waitcnt lgkmcnt(3)
	v_mfma_f32_16x16x32_bf16 v[92:95], v[172:175], v[140:143], 0
	v_mfma_f32_16x16x32_bf16 v[84:87], v[172:175], v[148:151], 0
	s_waitcnt lgkmcnt(1)
	v_mfma_f32_16x16x32_bf16 v[76:79], v[190:193], v[140:143], 0
	v_mfma_f32_16x16x32_bf16 v[68:71], v[190:193], v[148:151], 0
	v_mfma_f32_16x16x32_bf16 v[124:127], v[160:163], v[144:147], v[124:127]
	v_mfma_f32_16x16x32_bf16 v[116:119], v[160:163], v[152:155], v[116:119]
	v_mfma_f32_16x16x32_bf16 v[108:111], v[168:171], v[144:147], v[108:111]
	v_mfma_f32_16x16x32_bf16 v[100:103], v[168:171], v[152:155], v[100:103]
	v_mfma_f32_16x16x32_bf16 v[92:95], v[178:181], v[144:147], v[92:95]
	v_mfma_f32_16x16x32_bf16 v[84:87], v[178:181], v[152:155], v[84:87]
	s_waitcnt lgkmcnt(0)
	v_mfma_f32_16x16x32_bf16 v[76:79], v[194:197], v[144:147], v[76:79]
	v_mfma_f32_16x16x32_bf16 v[68:71], v[194:197], v[152:155], v[68:71]
	s_setprio 0
	s_barrier
	ds_read_b128 v[198:201], v136
	ds_read_b128 v[202:205], v136 offset:1024
	ds_read_b128 v[206:209], v136 offset:2048
	ds_read_b128 v[210:213], v136 offset:3072
	s_mov_b32 m0, s62
	s_nop 0
	global_load_lds_dwordx4 v130, s[94:95]
	s_mov_b32 m0, s63
	s_nop 0
	global_load_lds_dwordx4 v130, s[0:1]
	s_barrier
	s_setprio 1
	s_waitcnt lgkmcnt(3)
	v_mfma_f32_16x16x32_bf16 v[120:123], v[156:159], v[198:201], 0
	s_waitcnt lgkmcnt(1)
	v_mfma_f32_16x16x32_bf16 v[112:115], v[156:159], v[206:209], 0
	v_mfma_f32_16x16x32_bf16 v[104:107], v[164:167], v[198:201], 0
	v_mfma_f32_16x16x32_bf16 v[96:99], v[164:167], v[206:209], 0
	v_mfma_f32_16x16x32_bf16 v[88:91], v[172:175], v[198:201], 0
	v_mfma_f32_16x16x32_bf16 v[80:83], v[172:175], v[206:209], 0
	v_mfma_f32_16x16x32_bf16 v[72:75], v[190:193], v[198:201], 0
	v_mfma_f32_16x16x32_bf16 v[64:67], v[190:193], v[206:209], 0
	v_mfma_f32_16x16x32_bf16 v[120:123], v[160:163], v[202:205], v[120:123]
	s_waitcnt lgkmcnt(0)
	v_mfma_f32_16x16x32_bf16 v[112:115], v[160:163], v[210:213], v[112:115]
	v_mfma_f32_16x16x32_bf16 v[104:107], v[168:171], v[202:205], v[104:107]
	v_mfma_f32_16x16x32_bf16 v[96:99], v[168:171], v[210:213], v[96:99]
	v_mfma_f32_16x16x32_bf16 v[88:91], v[178:181], v[202:205], v[88:91]
	v_mfma_f32_16x16x32_bf16 v[80:83], v[178:181], v[210:213], v[80:83]
	v_mfma_f32_16x16x32_bf16 v[72:75], v[194:197], v[202:205], v[72:75]
	v_mfma_f32_16x16x32_bf16 v[64:67], v[194:197], v[210:213], v[64:67]
	s_setprio 0
	s_barrier
	ds_read_b128 v[156:159], v132 offset:16384
	ds_read_b128 v[160:163], v132 offset:17408
	ds_read_b128 v[164:167], v133 offset:16384
	ds_read_b128 v[168:171], v133 offset:17408
	ds_read_b128 v[172:175], v134 offset:16384
	ds_read_b128 v[178:181], v134 offset:17408
	ds_read_b128 v[190:193], v135 offset:16384
	ds_read_b128 v[194:197], v135 offset:17408
	s_mov_b32 m0, s59
	s_nop 0
	global_load_lds_dwordx4 v130, s[50:51]
	s_mov_b32 m0, s64
	s_nop 0
	global_load_lds_dwordx4 v130, s[52:53]
	s_barrier
	s_setprio 1
	s_waitcnt lgkmcnt(7)
	v_mfma_f32_16x16x32_bf16 v[60:63], v[156:159], v[140:143], 0
	v_mfma_f32_16x16x32_bf16 v[52:55], v[156:159], v[148:151], 0
	s_waitcnt lgkmcnt(5)
	v_mfma_f32_16x16x32_bf16 v[44:47], v[164:167], v[140:143], 0
	v_mfma_f32_16x16x32_bf16 v[36:39], v[164:167], v[148:151], 0
	s_waitcnt lgkmcnt(3)
	v_mfma_f32_16x16x32_bf16 v[28:31], v[172:175], v[140:143], 0
	v_mfma_f32_16x16x32_bf16 v[20:23], v[172:175], v[148:151], 0
	s_waitcnt lgkmcnt(1)
	v_mfma_f32_16x16x32_bf16 v[12:15], v[190:193], v[140:143], 0
	v_mfma_f32_16x16x32_bf16 v[4:7], v[190:193], v[148:151], 0
	v_mfma_f32_16x16x32_bf16 v[60:63], v[160:163], v[144:147], v[60:63]
	v_mfma_f32_16x16x32_bf16 v[52:55], v[160:163], v[152:155], v[52:55]
	v_mfma_f32_16x16x32_bf16 v[44:47], v[168:171], v[144:147], v[44:47]
	v_mfma_f32_16x16x32_bf16 v[36:39], v[168:171], v[152:155], v[36:39]
	v_mfma_f32_16x16x32_bf16 v[28:31], v[178:181], v[144:147], v[28:31]
	v_mfma_f32_16x16x32_bf16 v[20:23], v[178:181], v[152:155], v[20:23]
	s_waitcnt lgkmcnt(0)
	v_mfma_f32_16x16x32_bf16 v[12:15], v[194:197], v[144:147], v[12:15]
	v_mfma_f32_16x16x32_bf16 v[4:7], v[194:197], v[152:155], v[4:7]
	s_setprio 0
	s_barrier
; #define STAGE_A(Ak_, b, h) do { const char* _s = (Ak_) + (h) * sHA; \
;     glds16(lds0 + ((b) * 2 + (h)) * (HT * 2), voffA, _s); glds16(lds0 + ((b) * 2 + (h)) * (HT * 2) + 8192, voffA, _s + s2A); } while (0)
; #define STAGE_B(Bk_, Bkh_, vh_, b, h) do { const char* _s = (h) ? (Bkh_) : (Bk_); const unsigned _v0 = (h) ? (vh_)[0] : voffB, _v1 = (h) ? (vh_)[1] : voffB; const long _d = (h) ? s2Bh : s2B; \
;     glds16(lds0 + (4 + (b) * 2 + (h)) * (HT * 2), _v0, _s); glds16(lds0 + (4 + (b) * 2 + (h)) * (HT * 2) + 8192, _v1, _s + _d); } while (0)
; #define LDA(dst, b, h) for (int m = 0; m < 4; ++m) for (int k = 0; k < 2; ++k) \
;     dst[m][k] = *reinterpret_cast<const bf16x8*>((char*)SA(b, h) + lds_byte(wr * 64 + m * 16 + fr, k * 32 + fq * 8))
; #define LDB(dst, b, h) for (int n = 0; n < 2; ++n) for (int k = 0; k < 2; ++k) \
;     dst[n][k] = *reinterpret_cast<const bf16x8*>((char*)SB(b, h) + lds_byte(wc * 32 + n * 16 + fr, k * 32 + fq * 8))
; #define MMA(ai, bj, At_, Bt_) do { __builtin_amdgcn_s_setprio(1); \
;     for (int m = 0; m < 4; ++m) for (int n = 0; n < 2; ++n) for (int k = 0; k < 2; ++k) \
;       acc[ai][bj][m][n] = __builtin_amdgcn_mfma_f32_16x16x32_bf16(At_[m][k], Bt_[n][k], acc[ai][bj][m][n], 0, 0, 0); \
;     __builtin_amdgcn_s_setprio(0); } while (0)
; #define WAIT_V(n) asm volatile("s_waitcnt vmcnt(" #n ")" ::: "memory")
; #define WAIT_L(n) asm volatile("s_waitcnt lgkmcnt(" #n ")" ::: "memory")
; #define BAR __builtin_amdgcn_s_barrier()
; #define SCHED __builtin_amdgcn_sched_barrier(0)
; template <int EPI>
; __device__ __forceinline__ void gemm_phase(const GemmDesc d, u16* shm, unsigned sx, unsigned srank, unsigned snloc) {
;     ...
;         STAGE_B(B2, B2h, vh, 0, 1);
;         WAIT_V(6); BAR; MMA(1, 1, At, B1); BAR;
;         LDB(B0, 1, 0); SCHED; LDA(At, 1, 0); STAGE_A(A2, 0, 1);
;         WAIT_L(8); BAR; MMA(0, 0, At, B0); BAR; SCHED;
;         LDB(B1, 1, 1); STAGE_B(B3, B3h, vh, 1, 0);
;         BAR; MMA(0, 1, At, B1); BAR;
	s_mov_b32 m0, s65
	s_nop 0
	global_load_lds_dwordx4 v130, s[46:47]
	s_mov_b32 m0, s66
	s_nop 0
	global_load_lds_dwordx4 v130, s[48:49]
	s_waitcnt vmcnt(6)
	s_barrier
	s_setprio 1
	v_mfma_f32_16x16x32_bf16 v[56:59], v[156:159], v[198:201], 0
	v_mfma_f32_16x16x32_bf16 v[48:51], v[156:159], v[206:209], 0
	v_mfma_f32_16x16x32_bf16 v[40:43], v[164:167], v[198:201], 0
	v_mfma_f32_16x16x32_bf16 v[32:35], v[164:167], v[206:209], 0
	v_mfma_f32_16x16x32_bf16 v[24:27], v[172:175], v[198:201], 0
	v_mfma_f32_16x16x32_bf16 v[16:19], v[172:175], v[206:209], 0
	v_mfma_f32_16x16x32_bf16 v[8:11], v[190:193], v[198:201], 0
	v_mfma_f32_16x16x32_bf16 v[0:3], v[190:193], v[206:209], 0
	v_mfma_f32_16x16x32_bf16 v[56:59], v[160:163], v[202:205], v[56:59]
	v_mfma_f32_16x16x32_bf16 v[48:51], v[160:163], v[210:213], v[48:51]
	v_mfma_f32_16x16x32_bf16 v[40:43], v[168:171], v[202:205], v[40:43]
	v_mfma_f32_16x16x32_bf16 v[32:35], v[168:171], v[210:213], v[32:35]
	v_mfma_f32_16x16x32_bf16 v[24:27], v[178:181], v[202:205], v[24:27]
	v_mfma_f32_16x16x32_bf16 v[16:19], v[178:181], v[210:213], v[16:19]
	v_mfma_f32_16x16x32_bf16 v[8:11], v[194:197], v[202:205], v[8:11]
	v_mfma_f32_16x16x32_bf16 v[0:3], v[194:197], v[210:213], v[0:3]
	s_setprio 0
	s_barrier
	ds_read_b128 v[140:143], v137
	ds_read_b128 v[144:147], v137 offset:1024
	ds_read_b128 v[148:151], v137 offset:2048
	ds_read_b128 v[152:155], v137 offset:3072
	ds_read_b128 v[156:159], v132 offset:32768
	ds_read_b128 v[160:163], v132 offset:33792
	ds_read_b128 v[164:167], v133 offset:32768
	ds_read_b128 v[168:171], v133 offset:33792
	ds_read_b128 v[172:175], v134 offset:32768
	ds_read_b128 v[178:181], v134 offset:33792
	ds_read_b128 v[190:193], v135 offset:32768
	ds_read_b128 v[194:197], v135 offset:33792
	s_mov_b32 m0, s67
	s_nop 0
	global_load_lds_dwordx4 v130, s[44:45]
	s_mov_b32 m0, s69
	s_nop 0
	global_load_lds_dwordx4 v130, s[28:29]
	s_waitcnt lgkmcnt(8)
	s_barrier
	s_setprio 1
	s_waitcnt lgkmcnt(7)
	v_mfma_f32_16x16x32_bf16 v[124:127], v[156:159], v[140:143], v[124:127]
	v_mfma_f32_16x16x32_bf16 v[116:119], v[156:159], v[148:151], v[116:119]
	s_waitcnt lgkmcnt(5)
	v_mfma_f32_16x16x32_bf16 v[108:111], v[164:167], v[140:143], v[108:111]
	v_mfma_f32_16x16x32_bf16 v[100:103], v[164:167], v[148:151], v[100:103]
	s_waitcnt lgkmcnt(3)
	v_mfma_f32_16x16x32_bf16 v[92:95], v[172:175], v[140:143], v[92:95]
	v_mfma_f32_16x16x32_bf16 v[84:87], v[172:175], v[148:151], v[84:87]
	s_waitcnt lgkmcnt(1)
	v_mfma_f32_16x16x32_bf16 v[76:79], v[190:193], v[140:143], v[76:79]
	v_mfma_f32_16x16x32_bf16 v[68:71], v[190:193], v[148:151], v[68:71]
	v_mfma_f32_16x16x32_bf16 v[124:127], v[160:163], v[144:147], v[124:127]
	v_mfma_f32_16x16x32_bf16 v[116:119], v[160:163], v[152:155], v[116:119]
	v_mfma_f32_16x16x32_bf16 v[108:111], v[168:171], v[144:147], v[108:111]
	v_mfma_f32_16x16x32_bf16 v[100:103], v[168:171], v[152:155], v[100:103]
	v_mfma_f32_16x16x32_bf16 v[92:95], v[178:181], v[144:147], v[92:95]
	v_mfma_f32_16x16x32_bf16 v[84:87], v[178:181], v[152:155], v[84:87]
	s_waitcnt lgkmcnt(0)
	v_mfma_f32_16x16x32_bf16 v[76:79], v[194:197], v[144:147], v[76:79]
	v_mfma_f32_16x16x32_bf16 v[68:71], v[194:197], v[152:155], v[68:71]
	s_setprio 0
	s_barrier
	ds_read_b128 v[198:201], v138
	ds_read_b128 v[202:205], v138 offset:1024
	ds_read_b128 v[206:209], v138 offset:2048
	ds_read_b128 v[210:213], v138 offset:3072
	s_mov_b32 m0, s71
	s_nop 0
	global_load_lds_dwordx4 v130, s[40:41]
	s_mov_b32 m0, s72
	s_nop 0
	global_load_lds_dwordx4 v130, s[42:43]
	s_barrier
	s_setprio 1
	s_waitcnt lgkmcnt(3)
	v_mfma_f32_16x16x32_bf16 v[120:123], v[156:159], v[198:201], v[120:123]
	s_waitcnt lgkmcnt(1)
	v_mfma_f32_16x16x32_bf16 v[112:115], v[156:159], v[206:209], v[112:115]
	v_mfma_f32_16x16x32_bf16 v[104:107], v[164:167], v[198:201], v[104:107]
	v_mfma_f32_16x16x32_bf16 v[96:99], v[164:167], v[206:209], v[96:99]
	v_mfma_f32_16x16x32_bf16 v[88:91], v[172:175], v[198:201], v[88:91]
	v_mfma_f32_16x16x32_bf16 v[80:83], v[172:175], v[206:209], v[80:83]
	v_mfma_f32_16x16x32_bf16 v[72:75], v[190:193], v[198:201], v[72:75]
	v_mfma_f32_16x16x32_bf16 v[64:67], v[190:193], v[206:209], v[64:67]
	v_mfma_f32_16x16x32_bf16 v[120:123], v[160:163], v[202:205], v[120:123]
	s_waitcnt lgkmcnt(0)
	v_mfma_f32_16x16x32_bf16 v[112:115], v[160:163], v[210:213], v[112:115]
	v_mfma_f32_16x16x32_bf16 v[104:107], v[168:171], v[202:205], v[104:107]
	v_mfma_f32_16x16x32_bf16 v[96:99], v[168:171], v[210:213], v[96:99]
	v_mfma_f32_16x16x32_bf16 v[88:91], v[178:181], v[202:205], v[88:91]
	v_mfma_f32_16x16x32_bf16 v[80:83], v[178:181], v[210:213], v[80:83]
	v_mfma_f32_16x16x32_bf16 v[72:75], v[194:197], v[202:205], v[72:75]
	v_mfma_f32_16x16x32_bf16 v[64:67], v[194:197], v[210:213], v[64:67]
	s_setprio 0
	s_barrier
; #define STAGE_A(Ak_, b, h) do { const char* _s = (Ak_) + (h) * sHA; \
;     glds16(lds0 + ((b) * 2 + (h)) * (HT * 2), voffA, _s); glds16(lds0 + ((b) * 2 + (h)) * (HT * 2) + 8192, voffA, _s + s2A); } while (0)
; #define STAGE_B(Bk_, Bkh_, vh_, b, h) do { const char* _s = (h) ? (Bkh_) : (Bk_); const unsigned _v0 = (h) ? (vh_)[0] : voffB, _v1 = (h) ? (vh_)[1] : voffB; const long _d = (h) ? s2Bh : s2B; \
;     glds16(lds0 + (4 + (b) * 2 + (h)) * (HT * 2), _v0, _s); glds16(lds0 + (4 + (b) * 2 + (h)) * (HT * 2) + 8192, _v1, _s + _d); } while (0)
; #define LDA(dst, b, h) for (int m = 0; m < 4; ++m) for (int k = 0; k < 2; ++k) \
;     dst[m][k] = *reinterpret_cast<const bf16x8*>((char*)SA(b, h) + lds_byte(wr * 64 + m * 16 + fr, k * 32 + fq * 8))
; #define MMA(ai, bj, At_, Bt_) do { __builtin_amdgcn_s_setprio(1); \
;     for (int m = 0; m < 4; ++m) for (int n = 0; n < 2; ++n) for (int k = 0; k < 2; ++k) \
;       acc[ai][bj][m][n] = __builtin_amdgcn_mfma_f32_16x16x32_bf16(At_[m][k], Bt_[n][k], acc[ai][bj][m][n], 0, 0, 0); \
;     __builtin_amdgcn_s_setprio(0); } while (0)
; #define WAIT_V(n) asm volatile("s_waitcnt vmcnt(" #n ")" ::: "memory")
; #define BAR __builtin_amdgcn_s_barrier()
; #define SCHED __builtin_amdgcn_sched_barrier(0)
; template <int EPI>
; __device__ __forceinline__ void gemm_phase(const GemmDesc d, u16* shm, unsigned sx, unsigned srank, unsigned snloc) {
;     ...
;         const bool lastk = (kt + 2 >= nt);
;         const char* A1 = Au + (long)(kt + 1) * sKA;
;         const char* A2 = lastk ? Aun : Au + (long)(kt + 2) * sKA;
;         const char* B2 = lastk ? Bun : Bu + (long)(kt + 2) * sKB;
;         const char* B2h = lastk ? Bunh : Buh + (long)(kt + 2) * sKB;
;         const unsigned vh[2] = {lastk ? voffBhn[0] : voffBh[0], lastk ? voffBhn[1] : voffBh[1]};
;         const char* A3 = A2 + sKA; const char* B3 = B2 + sKB; const char* B3h = B2h + sKB;
;     ...
;         LDA(At, 1, 1); STAGE_A(A3, 1, 0);
;         BAR; MMA(1, 0, At, B0); BAR; SCHED;
;         STAGE_B(B3, B3h, vh, 1, 1);
;         WAIT_V(6); BAR; MMA(1, 1, At, B1); BAR;
	ds_read_b128 v[156:159], v132 offset:49152
	ds_read_b128 v[160:163], v132 offset:50176
	ds_read_b128 v[164:167], v133 offset:49152
	ds_read_b128 v[168:171], v133 offset:50176
	ds_read_b128 v[172:175], v134 offset:49152
	ds_read_b128 v[178:181], v134 offset:50176
	ds_read_b128 v[190:193], v135 offset:49152
	ds_read_b128 v[194:197], v135 offset:50176
	s_mov_b32 m0, s73
	s_nop 0
	global_load_lds_dwordx4 v130, s[22:23]
	s_mov_b32 m0, s76
	s_nop 0
	global_load_lds_dwordx4 v130, s[30:31]
	s_barrier
	s_setprio 1
	s_waitcnt lgkmcnt(7)
	v_mfma_f32_16x16x32_bf16 v[60:63], v[156:159], v[140:143], v[60:63]
	v_mfma_f32_16x16x32_bf16 v[52:55], v[156:159], v[148:151], v[52:55]
	s_waitcnt lgkmcnt(5)
	v_mfma_f32_16x16x32_bf16 v[44:47], v[164:167], v[140:143], v[44:47]
	v_mfma_f32_16x16x32_bf16 v[36:39], v[164:167], v[148:151], v[36:39]
	s_waitcnt lgkmcnt(3)
	v_mfma_f32_16x16x32_bf16 v[28:31], v[172:175], v[140:143], v[28:31]
	v_mfma_f32_16x16x32_bf16 v[20:23], v[172:175], v[148:151], v[20:23]
	s_waitcnt lgkmcnt(1)
	v_mfma_f32_16x16x32_bf16 v[12:15], v[190:193], v[140:143], v[12:15]
	v_mfma_f32_16x16x32_bf16 v[4:7], v[190:193], v[148:151], v[4:7]
	v_mfma_f32_16x16x32_bf16 v[60:63], v[160:163], v[144:147], v[60:63]
	v_mfma_f32_16x16x32_bf16 v[52:55], v[160:163], v[152:155], v[52:55]
	v_mfma_f32_16x16x32_bf16 v[44:47], v[168:171], v[144:147], v[44:47]
	v_mfma_f32_16x16x32_bf16 v[36:39], v[168:171], v[152:155], v[36:39]
	v_mfma_f32_16x16x32_bf16 v[28:31], v[178:181], v[144:147], v[28:31]
	v_mfma_f32_16x16x32_bf16 v[20:23], v[178:181], v[152:155], v[20:23]
	s_waitcnt lgkmcnt(0)
	v_mfma_f32_16x16x32_bf16 v[12:15], v[194:197], v[144:147], v[12:15]
	v_mfma_f32_16x16x32_bf16 v[4:7], v[194:197], v[152:155], v[4:7]
	s_setprio 0
	s_barrier
	s_mov_b32 m0, s77
	s_nop 0
	global_load_lds_dwordx4 v130, s[18:19]
	s_mov_b32 m0, s78
	s_nop 0
	global_load_lds_dwordx4 v130, s[4:5]
	s_mov_b64 s[34:35], s[38:39]
	s_mov_b32 s20, s21
	s_add_i32 s21, s20, 2
	s_add_u32 s0, s34, 0xfffc0080
	s_addc_u32 s1, s35, -1
	s_cmp_lt_u32 s20, 14
	s_cselect_b32 s94, s90, s16
	s_cselect_b32 s51, s1, s15
	s_cselect_b32 s50, s0, s14
	s_cselect_b32 s95, s91, s17
	s_cselect_b32 s47, s93, s25
	s_cselect_b32 s46, s92, s24
	s_add_u32 s40, s94, 0x80
	s_addc_u32 s41, s95, 0
	s_add_u32 s22, s50, 0x80
	s_addc_u32 s23, s51, 0
	s_add_u32 s96, s34, 0x20000
	s_addc_u32 s97, s35, 0
	s_add_u32 s0, s94, 0x20000
	s_addc_u32 s1, s95, 0
	s_add_u32 s52, s50, 0x20000
	s_addc_u32 s53, s51, 0
	s_add_u32 s48, s46, 0x20000
	s_addc_u32 s49, s47, 0
	s_add_u32 s44, s50, 0x40000
	s_addc_u32 s45, s51, 0
	s_add_u32 s28, s50, 0x60000
	s_addc_u32 s29, s51, 0
	s_add_u32 s42, s94, 0x20080
	s_addc_u32 s43, s95, 0
	s_add_u32 s30, s50, 0x20080
	s_addc_u32 s31, s51, 0
	s_add_u32 s18, s46, 0x80
	s_addc_u32 s19, s47, 0
	s_add_u32 s4, s46, 0x20080
	s_addc_u32 s5, s47, 0
	s_add_u32 s38, s34, 0x100
	s_addc_u32 s39, s35, 0
	s_add_u32 s90, s90, 0x100
	s_addc_u32 s91, s91, 0
	s_add_u32 s92, s92, 0x100
	s_addc_u32 s93, s93, 0
	s_waitcnt vmcnt(6)
	s_barrier
	s_setprio 1
	v_mfma_f32_16x16x32_bf16 v[56:59], v[156:159], v[198:201], v[56:59]
	v_mfma_f32_16x16x32_bf16 v[48:51], v[156:159], v[206:209], v[48:51]
	v_mfma_f32_16x16x32_bf16 v[40:43], v[164:167], v[198:201], v[40:43]
	v_mfma_f32_16x16x32_bf16 v[32:35], v[164:167], v[206:209], v[32:35]
	v_mfma_f32_16x16x32_bf16 v[24:27], v[172:175], v[198:201], v[24:27]
	v_mfma_f32_16x16x32_bf16 v[16:19], v[172:175], v[206:209], v[16:19]
	v_mfma_f32_16x16x32_bf16 v[8:11], v[190:193], v[198:201], v[8:11]
	v_mfma_f32_16x16x32_bf16 v[0:3], v[190:193], v[206:209], v[0:3]
	v_mfma_f32_16x16x32_bf16 v[56:59], v[160:163], v[202:205], v[56:59]
	v_mfma_f32_16x16x32_bf16 v[48:51], v[160:163], v[210:213], v[48:51]
	v_mfma_f32_16x16x32_bf16 v[40:43], v[168:171], v[202:205], v[40:43]
	v_mfma_f32_16x16x32_bf16 v[32:35], v[168:171], v[210:213], v[32:35]
	v_mfma_f32_16x16x32_bf16 v[24:27], v[178:181], v[202:205], v[24:27]
	v_mfma_f32_16x16x32_bf16 v[16:19], v[178:181], v[210:213], v[16:19]
	v_mfma_f32_16x16x32_bf16 v[8:11], v[194:197], v[202:205], v[8:11]
	v_mfma_f32_16x16x32_bf16 v[0:3], v[194:197], v[210:213], v[0:3]
	s_setprio 0
	s_barrier

; #define BAR __builtin_amdgcn_s_barrier()
; template <int EPI>
; __device__ __forceinline__ void gemm_phase(const GemmDesc d, u16* shm, unsigned sx, unsigned srank, unsigned snloc) {
;     ...
;       if (!has_next) break;
;       t = tn; z = zn; pm = pmn; pn = pnn; Au = Aun; Bu = Bun; Buh = Bunh; voffBh[0] = voffBhn[0]; voffBh[1] = voffBhn[1];
;       if (wr == 1) BAR;
.LBB0_1454:
	s_or_b64 exec, exec, s[4:5]
	s_andn2_b64 vcc, exec, s[26:27]
	s_mov_b64 s[4:5], -1
	s_cbranch_vccnz .LBB0_1443
	s_branch .LBB0_1442
